# P0 transposed bf16 weight stores with the nt policy (on top of nt2)
# speedup vs baseline: 1.0009x; 1.0009x over previous
; #define LAS __attribute__((address_space(3)))
; #define LDS_WAIT() asm volatile("s_waitcnt lgkmcnt(0)" ::: "memory")
; __device__ __forceinline__ unsigned pk2(float lo, float hi) { unsigned r; asm("v_cvt_pk_bf16_f32 %0, %1, %2" : "=v"(r) : "v"(lo), "v"(hi)); return r; }
; __device__ __forceinline__ void p0_transpose_item(const float* W, int K, int N, bf16_t* WT, LAS float* scr, int item, int lane, const float* kscale) {
;     const int nblk = N / 32, kb = item / nblk, nb = item % nblk, k0 = 64 * kb, n0 = 32 * nb;
; #pragma unroll 8
;     for (int i = 0; i < 32; ++i) { const int kk = 2 * i + (lane >> 5); scr[kk * 33 + (lane & 31)] = W[(size_t)(k0 + kk) * N + n0 + (lane & 31)] * (kscale ? kscale[k0 + kk] : 1.0f); }
;     LDS_WAIT(); asm volatile("" ::: "memory");
;     const int c = lane & 7;
; #pragma unroll
;     for (int j = 0; j < 4; ++j) { const int n = (lane >> 3) + 8 * j; const LAS float* s = scr + (8 * c) * 33 + n;
;         v4u o; o.x = pk2(s[0 * 33], s[1 * 33]); o.y = pk2(s[2 * 33], s[3 * 33]); o.z = pk2(s[4 * 33], s[5 * 33]); o.w = pk2(s[6 * 33], s[7 * 33]);
;         *(v4u*)(WT + (size_t)(n0 + n) * K + k0 + 8 * c) = o; }
;     LDS_WAIT(); asm volatile("" ::: "memory");
; }
.LBB0_224:
	s_mul_i32 s1, s2, 0x1a00000
	s_waitcnt lgkmcnt(0)
	s_mul_hi_i32 s0, s2, 0x1a00000
	s_add_u32 s2, s94, s1
	s_addc_u32 s3, s95, s0
	s_lshl_b64 s[0:1], s[20:21], 1
	ds_read2_b32 v[18:19], v9 offset0:33 offset1:41
	ds_read2_b32 v[20:21], v9 offset1:8
	ds_read2_b32 v[22:23], v9 offset0:66 offset1:74
	ds_read2_b32 v[24:25], v9 offset0:99 offset1:107
	ds_read2_b32 v[26:27], v9 offset0:132 offset1:140
	ds_read2_b32 v[28:29], v9 offset0:165 offset1:173
	ds_read2_b32 v[30:31], v9 offset0:198 offset1:206
	ds_read2_b32 v[32:33], v9 offset0:231 offset1:239
	s_add_u32 s0, s2, s0
	v_or_b32_e32 v48, s16, v7
	s_addc_u32 s1, s3, s1
	v_lshlrev_b32_e32 v0, 1, v8
	v_ashrrev_i32_e32 v49, 31, v48
	v_lshl_add_u64 v[34:35], s[0:1], 0, v[0:1]
	v_lshlrev_b64 v[48:49], 12, v[48:49]
	s_waitcnt lgkmcnt(6)
	v_cvt_pk_bf16_f32 v14, v20, v18
	v_lshl_add_u64 v[48:49], v[34:35], 0, v[48:49]
	v_or_b32_e32 v18, s16, v36
	s_waitcnt lgkmcnt(4)
	v_cvt_pk_bf16_f32 v15, v22, v24
	s_waitcnt lgkmcnt(2)
	v_cvt_pk_bf16_f32 v16, v26, v28
	s_waitcnt lgkmcnt(0)
	v_cvt_pk_bf16_f32 v17, v30, v32
	global_store_dwordx4 v[48:49], v[14:17], off nt
	s_nop 1
	v_cvt_pk_bf16_f32 v14, v21, v19
	v_ashrrev_i32_e32 v19, 31, v18
	v_lshlrev_b64 v[18:19], 12, v[18:19]
	v_cvt_pk_bf16_f32 v15, v23, v25
	v_cvt_pk_bf16_f32 v16, v27, v29
	v_cvt_pk_bf16_f32 v17, v31, v33
	v_lshl_add_u64 v[18:19], v[34:35], 0, v[18:19]
	ds_read2_b32 v[20:21], v9 offset0:16 offset1:24
	ds_read2_b32 v[22:23], v9 offset0:49 offset1:57
	ds_read2_b32 v[24:25], v9 offset0:82 offset1:90
	ds_read2_b32 v[26:27], v9 offset0:115 offset1:123
	ds_read2_b32 v[28:29], v9 offset0:148 offset1:156
	ds_read2_b32 v[30:31], v9 offset0:181 offset1:189
	ds_read2_b32 v[32:33], v9 offset0:214 offset1:222
	ds_read2_b32 v[48:49], v9 offset0:247 offset1:255
	global_store_dwordx4 v[18:19], v[14:17], off nt
	v_or_b32_e32 v18, s16, v37
	v_ashrrev_i32_e32 v19, 31, v18
	v_lshlrev_b64 v[18:19], 12, v[18:19]
	v_lshl_add_u64 v[18:19], v[34:35], 0, v[18:19]
	s_waitcnt lgkmcnt(6)
	v_cvt_pk_bf16_f32 v14, v20, v22
	s_waitcnt lgkmcnt(4)
	v_cvt_pk_bf16_f32 v15, v24, v26
	s_waitcnt lgkmcnt(2)
	v_cvt_pk_bf16_f32 v16, v28, v30
	s_waitcnt lgkmcnt(0)
	v_cvt_pk_bf16_f32 v17, v32, v48
	global_store_dwordx4 v[18:19], v[14:17], off nt
	v_or_b32_e32 v18, s16, v38
	v_ashrrev_i32_e32 v19, 31, v18
	v_lshlrev_b64 v[18:19], 12, v[18:19]
	v_lshl_add_u64 v[18:19], v[34:35], 0, v[18:19]
	v_cvt_pk_bf16_f32 v14, v21, v23
	v_cvt_pk_bf16_f32 v15, v25, v27
	v_cvt_pk_bf16_f32 v16, v29, v31
	v_cvt_pk_bf16_f32 v17, v33, v49
	global_store_dwordx4 v[18:19], v[14:17], off nt
	s_waitcnt lgkmcnt(0)
